# stack6 + K-tile LDS swizzle on (row&15): conflict-free ds_read_b128 of K fragments in attention
# baseline (speedup 1.0000x reference)
.LBB0_503:
	s_cmp_lt_i32 s54, 4
	s_cselect_b64 s[8:9], -1, 0
	s_add_u32 s58, s18, 0xb400000
	s_addc_u32 s59, s19, 0
	s_and_b64 s[0:1], s[8:9], s[6:7]
	s_cmpk_lt_i32 s64, 0x100
	s_cselect_b64 s[2:3], -1, 0
	s_and_b64 s[0:1], s[0:1], s[2:3]
	s_andn2_b64 vcc, exec, s[0:1]
	s_cbranch_vccnz .LBB0_537
	v_lshrrev_b32_e32 v7, 3, v0
	v_lshrrev_b32_e32 v5, 4, v0
	v_and_b32_e32 v7, 8, v7
	v_lshlrev_b32_e32 v4, 3, v0
	v_and_or_b32 v8, v5, 16, v7
	v_and_b32_e32 v6, 0x78, v4
	v_lshrrev_b32_e32 v9, 5, v0
	v_lshrrev_b32_e32 v8, 1, v8
	v_bfe_u32 v10, v4, 5, 2
	v_bfe_u32 v11, v0, 4, 2
	v_or_b32_e32 v8, v8, v10
	v_and_or_b32 v9, v9, 4, v11
	v_lshlrev_b32_e32 v11, 1, v6
	v_lshlrev_b32_e32 v8, 9, v8
	v_lshlrev_b32_e32 v9, 6, v9
	v_and_b32_e32 v12, 48, v11
	v_or3_b32 v13, v8, v9, v12
	v_or_b32_e32 v8, 32, v5
	v_and_or_b32 v7, v8, 48, v7
	v_lshrrev_b32_e32 v7, 1, v7
	v_or_b32_e32 v7, v7, v10
	v_lshlrev_b32_e32 v7, 9, v7
	v_or3_b32 v7, v7, v9, v12
	v_lshlrev_b32_e32 v9, 4, v0
	v_lshlrev_b32_e32 v12, 1, v0
	v_lshrrev_b32_e32 v3, 5, v1
	v_and_b32_e32 v10, 0xc0, v9
	v_and_b32_e32 v12, 32, v12
	v_and_b32_e32 v4, 0x118, v4
	s_lshl_b32 s0, s64, 1
	v_and_b32_e32 v181, 31, v0
	v_or3_b32 v15, v12, v10, v4
	v_lshl_or_b32 v4, v5, 9, v6
	v_lshl_or_b32 v6, v8, 9, v6
	v_lshlrev_b32_e32 v10, 8, v5
	v_and_b32_e32 v12, 0xf0, v0
	v_lshlrev_b32_e32 v8, 8, v8
	v_lshlrev_b32_e32 v195, 4, v3
	s_cmp_lg_u32 0, -1
	v_bitop3_b32 v17, v11, v10, v12 bitop3:0xde
	v_bitop3_b32 v11, v11, v8, v12 bitop3:0xde
	v_lshlrev_b32_e32 v8, 8, v181
	v_and_b32_e32 v10, 0xf0, v9
	v_or_b32_e32 v12, 32, v195
	s_cselect_b32 s6, 0, 0
	v_bitop3_b32 v19, v12, v8, v10 bitop3:0xde
	v_or_b32_e32 v12, 64, v195
	v_add_u32_e32 v194, s6, v15
	v_bitop3_b32 v20, v12, v8, v10 bitop3:0xde
	v_or_b32_e32 v12, 0x60, v195
	s_addk_i32 s6, 0x4000
	v_bitop3_b32 v21, v12, v8, v10 bitop3:0xde
	v_or_b32_e32 v12, 0x80, v195
	v_add_u32_e32 v196, s6, v15
	s_load_dword s6, s[90:91], 0xe0
	v_bitop3_b32 v22, v12, v8, v10 bitop3:0xde
	v_or_b32_e32 v12, 0xa0, v195
	v_lshlrev_b32_e32 v2, 3, v3
	v_bitop3_b32 v23, v12, v8, v10 bitop3:0xde
	v_or_b32_e32 v12, 0xc0, v195
	v_lshlrev_b32_e32 v197, 10, v3
	v_and_b32_e32 v3, 15, v0
	v_bitop3_b32 v24, v12, v8, v10 bitop3:0xde
	v_or_b32_e32 v12, 0xe0, v195
	v_cmp_gt_u32_e64 s[4:5], 32, v1
	v_lshrrev_b32_e32 v1, 4, v1
	v_lshlrev_b32_e32 v200, 4, v3
	v_mov_b32_e32 v179, 0
	v_bitop3_b32 v18, v195, v8, v10 bitop3:0xde
	v_bitop3_b32 v25, v12, v8, v10 bitop3:0xde
	v_or_b32_e32 v8, 0x8000, v4
	v_or_b32_e32 v10, 0xc000, v4
	v_or_b32_e32 v12, 0x14000, v4
	v_or_b32_e32 v14, 0x10000, v4
	v_lshlrev_b32_e32 v16, 11, v1
	v_lshl_or_b32 v178, v5, 10, v200
	s_mov_b32 s11, 0
	s_mov_b32 s1, 0x8000
	s_mov_b32 s2, 0xc000
	s_mov_b32 s3, 0x14000
	s_mov_b32 s13, 0x10000
	s_movk_i32 s14, 0x4000
	v_lshlrev_b32_e32 v198, 1, v181
	v_lshlrev_b32_e32 v180, 3, v3
	v_lshlrev_b32_e32 v199, 8, v1
	v_bfe_u32 v201, v0, 2, 1
	v_and_b32_e32 v202, 48, v9
	s_waitcnt lgkmcnt(0)
	s_lshl_b32 s15, s6, 1
	v_lshl_add_u64 v[182:183], s[18:19], 0, v[178:179]
	v_lshlrev_b32_e32 v184, 1, v2
	v_lshlrev_b32_e32 v203, 1, v4
	v_lshlrev_b32_e32 v204, 1, v6
	s_mov_b32 s16, 0x42b504f3
	v_lshlrev_b32_e32 v205, 1, v8
	v_lshlrev_b32_e32 v206, 1, v10
	v_lshlrev_b32_e32 v207, 1, v12
	v_lshlrev_b32_e32 v208, 1, v14
	s_mov_b32 s12, 0x3e0293ee
	s_mov_b32 s17, 0x30000
	s_mov_b32 s20, 0x38000
	s_mov_b64 s[64:65], 0x20000
	v_lshlrev_b32_e32 v178, 1, v16
	s_mov_b32 s21, 0x3ffe0
	s_mov_b32 s22, 0x18000
	s_mov_b32 s23, 0x1c000
	v_mov_b32_e32 v185, v179
	v_add_u32_e32 v209, 0, v13
	v_add_u32_e32 v210, 0, v7
	v_add_u32_e32 v211, 0, v17
	v_add_u32_e32 v212, 0, v11
	v_add_u32_e32 v213, 0, v18
	v_add_u32_e32 v214, 0, v19
	v_add_u32_e32 v215, 0, v20
	v_add_u32_e32 v216, 0, v21
	v_add_u32_e32 v217, 0, v22
	v_add_u32_e32 v218, 0, v23
	v_add_u32_e32 v219, 0, v24
	v_add_u32_e32 v220, 0, v25
	v_mov_b32_e32 v221, 0xf149f2ca
	s_branch .LBB0_506
